# stick-breaking loop: per-iteration LDS continue-flag accessed with ds_write/ds_read instead of flat ops (no vmcnt drain mid-iteration)
# baseline (speedup 1.0000x reference)
; DI unsigned pack2(float a, float b) { f32x2 v = {a, b}; return __builtin_bit_cast(unsigned, __builtin_convertvector(v, hwbf16x2)); }
; DI void sb_item(const bf16_t* __restrict__ P, const bf16_t* __restrict__ VT, bf16_t* __restrict__ Y, int item, char* lds) {
;     ...
;   bf16_t* yp = Y + (tokbase + qpos) * DM + hd * 64 + 4 * hh;
; #pragma unroll
;   for (int dt = 0; dt < 2; ++dt)
; #pragma unroll
;     for (int j = 0; j < 4; ++j) {
;       u32x2 v; v.x = pack2(O[dt][4 * j], O[dt][4 * j + 1]); v.y = pack2(O[dt][4 * j + 2], O[dt][4 * j + 3]);
;       *(u32x2*)(yp + dt * 32 + 8 * j) = v;
;     }
.LBB0_482:
	s_or_b64 exec, exec, s[34:35]
	s_waitcnt vmcnt(0)
	v_lshlrev_b64 v[2:3], 11, v[114:115]
	v_lshl_add_u64 v[2:3], s[64:65], 0, v[2:3]
	s_lshl_b32 s28, s11, 1
	v_lshl_add_u64 v[2:3], v[2:3], 0, s[28:29]
	v_lshlrev_b32_e32 v0, 1, v113
	v_lshl_add_u64 v[2:3], v[2:3], 0, v[0:1]
	v_mbcnt_lo_u32_b32 v0, -1, 0
	v_mbcnt_hi_u32_b32 v0, -1, v0
	v_and_b32_e32 v0, 32, v0
	v_lshrrev_b32_e32 v0, 2, v0
	v_mov_b32_e32 v1, 0
	v_lshl_add_u64 v[2:3], v[2:3], 0, v[0:1]
	v_cvt_pk_bf16_f32 v32, v32, v33
	v_cvt_pk_bf16_f32 v33, v34, v35
	v_cvt_pk_bf16_f32 v34, v36, v37
	v_cvt_pk_bf16_f32 v35, v38, v39
	s_nop 1
	v_permlane32_swap_b32_e32 v32, v34
	v_permlane32_swap_b32_e32 v33, v35
	global_store_dwordx4 v[2:3], v[32:35], off
	v_cvt_pk_bf16_f32 v36, v40, v41
	v_cvt_pk_bf16_f32 v37, v42, v43
	v_cvt_pk_bf16_f32 v38, v44, v45
	v_cvt_pk_bf16_f32 v39, v46, v47
	s_nop 1
	v_permlane32_swap_b32_e32 v36, v38
	v_permlane32_swap_b32_e32 v37, v39
	global_store_dwordx4 v[2:3], v[36:39], off offset:32
	v_cvt_pk_bf16_f32 v16, v16, v17
	v_cvt_pk_bf16_f32 v17, v18, v19
	v_cvt_pk_bf16_f32 v18, v20, v21
	v_cvt_pk_bf16_f32 v19, v22, v23
	s_nop 1
	v_permlane32_swap_b32_e32 v16, v18
	v_permlane32_swap_b32_e32 v17, v19
	global_store_dwordx4 v[2:3], v[16:19], off offset:64
	s_add_i32 s8, s8, s78
	s_add_i32 s7, s7, s78
	v_cvt_pk_bf16_f32 v20, v24, v25
	v_cvt_pk_bf16_f32 v21, v26, v27
	v_cvt_pk_bf16_f32 v22, v28, v29
	v_cvt_pk_bf16_f32 v23, v30, v31
	s_nop 1
	v_permlane32_swap_b32_e32 v20, v22
	v_permlane32_swap_b32_e32 v21, v23
	global_store_dwordx4 v[2:3], v[20:23], off offset:96
	s_cmpk_gt_i32 s8, 0x7ff
	s_cbranch_scc1 .LBB0_477

; DI void sb_item(const bf16_t* __restrict__ P, const bf16_t* __restrict__ VT, bf16_t* __restrict__ Y, int item, char* lds) {
;     ...
;     if (carry > 0.f) flags[fi] = 1;
;     __syncthreads();
;     const int cont = flags[fi];
;     const int fz = fi >= 1 ? fi - 1 : 2;
;     if (tid == 0) flags[fz] = 0;
;     fi = fi == 2 ? 0 : fi + 1;
;     if (!cont) break;
.LBB0_491:
	s_or_b64 exec, exec, s[48:49]
	v_cmp_lt_f32_e32 vcc, 0, v117
	s_and_saveexec_b64 s[0:1], vcc
	s_cbranch_execz .LBB0_493
	s_mov_b64 s[14:15], src_shared_base
	s_lshl_b32 s14, s13, 2
	s_add_i32 s14, s14, 0x24010
	v_mov_b32_e32 v2, s14
	v_mov_b32_e32 v3, s15
	ds_write_b32 v2, v176
	s_waitcnt lgkmcnt(0)
.LBB0_493:
	s_or_b64 exec, exec, s[0:1]
	s_mov_b64 s[0:1], src_shared_base
	s_lshl_b32 s0, s13, 2
	s_add_i32 s0, s0, 0x24010
	v_mov_b32_e32 v2, s0
	v_mov_b32_e32 v3, s1
	s_waitcnt lgkmcnt(0)
	s_barrier
	ds_read_b32 v0, v2
	s_waitcnt lgkmcnt(0)
	s_and_saveexec_b64 s[0:1], s[42:43]
	s_cbranch_execz .LBB0_495
	s_mov_b64 s[14:15], src_shared_base
	s_add_i32 s14, s13, -1
	s_cmp_gt_i32 s13, 0
	s_cselect_b32 s14, s14, 2
	s_lshl_b32 s14, s14, 2
	s_add_i32 s14, s14, 0x24010
	v_mov_b32_e32 v2, s14
	v_mov_b32_e32 v3, s15
	ds_write_b32 v2, v1
	s_waitcnt lgkmcnt(0)
